# GEMM loops: all per-phase s_setprio flips removed (A/B before a static raise for waves 4-7)
# speedup vs baseline: 1.0049x; 1.0049x over previous
; #define PG8_STAGE(bufoff, gbase, voff) do { _Pragma("unroll") for (int _i = 0; _i < 2; ++_i) \
;         __builtin_amdgcn_global_load_lds((const unsigned*)((const char*)(gbase) + (voff)[_i]), (PG8_LAS unsigned*)(lds + (bufoff) + ldsw + _i * 8192), 16, 0, 0); } while (0)
; #define PG8_LDA(dst, b, h) do { _Pragma("unroll") for (int m = 0; m < 4; ++m) _Pragma("unroll") for (int k = 0; k < 2; ++k) dst[m][k] = *(const PG8_LAS bf16x8*)(lds + PG8_SA(b, h) + aoff + m * 2048 + k * 1024); } while (0)
; #define PG8_LDB(dst, b, h) do { _Pragma("unroll") for (int n = 0; n < 2; ++n) _Pragma("unroll") for (int k = 0; k < 2; ++k) dst[n][k] = *(const PG8_LAS bf16x8*)(lds + PG8_SB(b, h) + boff + n * 2048 + k * 1024); } while (0)
; #define PG8_MMA(ai, bj, At, Bt) do { __builtin_amdgcn_s_setprio(1); _Pragma("unroll") for (int m = 0; m < 4; ++m) _Pragma("unroll") for (int n = 0; n < 2; ++n) _Pragma("unroll") for (int k = 0; k < 2; ++k) \
;         acc[ai][bj][m][n] = __builtin_amdgcn_mfma_f32_16x16x32_bf16(Bt[n][k], At[m][k], acc[ai][bj][m][n], 0, 0, 0); __builtin_amdgcn_s_setprio(0); } while (0)
; #define PG8_WAIT_V(n) asm volatile("s_waitcnt vmcnt(" #n ")" ::: "memory")
; #define PG8_WAIT_L(n) asm volatile("s_waitcnt lgkmcnt(" #n ")" ::: "memory")
; #define PG8_BAR __builtin_amdgcn_s_barrier()
; #define PG8_SCHED __builtin_amdgcn_sched_barrier(0)
; template <class Epi, class Sched, bool ALIGN_EPI = false, bool SP2 = false>
; __device__ __forceinline__ void gemm_phase(PG8_LAS unsigned char* lds, const Gemm g, const Sched& S, const Epi& E) {
;     ...
;             PG8_LDB(B0, 0, 0); PG8_LDB(B1, 0, 1); PG8_SCHED; PG8_LDA(At, 0, 0); PG8_STAGE(PG8_SA(1, 1), a1 + hstep, voffA);
;             PG8_WAIT_V(8); PG8_WAIT_L(0); PG8_BAR; PG8_MMA(0, 0, At, B0); PG8_MMA(0, 1, At, B1); PG8_BAR; PG8_SCHED;
;             PG8_LDA(At, 0, 1); PG8_STAGE(PG8_SB(0, 0), b2, voffB); PG8_STAGE(PG8_SB(0, 1), b2 + hstep, voffB); PG8_STAGE(PG8_SA(0, 0), a2, voffA);
;             PG8_WAIT_V(8); PG8_WAIT_L(0); PG8_BAR; PG8_MMA(1, 0, At, B0); PG8_MMA(1, 1, At, B1); PG8_BAR; PG8_SCHED;
.LBB0_67:
	s_add_i32 s81, s81, 2
	s_add_u32 vcc_lo, s46, 0x80
	s_addc_u32 vcc_hi, s47, 0
	s_and_b64 s[14:15], s[48:49], exec
	s_cselect_b32 s49, s57, vcc_hi
	s_cselect_b32 s48, s56, vcc_lo
	s_cselect_b32 s15, s59, s83
	s_cselect_b32 s14, s58, s3
	s_add_i32 vcc_lo, 0, 0x10000
	v_add_u32_e32 v3, vcc_lo, v196
	s_add_i32 vcc_hi, 0, 0x14000
	ds_read_b128 v[64:67], v3
	ds_read_b128 v[148:151], v3 offset:1024
	ds_read_b128 v[152:155], v3 offset:2048
	ds_read_b128 v[156:159], v3 offset:3072
	v_add_u32_e32 v3, vcc_hi, v196
	ds_read_b128 v[160:163], v3
	ds_read_b128 v[164:167], v3 offset:1024
	ds_read_b128 v[168:171], v3 offset:2048
	ds_read_b128 v[188:191], v3 offset:3072
	v_lshl_add_u64 v[192:193], s[46:47], 0, v[184:185]
	s_add_i32 m0, s62, 0xc000
	ds_read_b128 v[198:201], v197
	ds_read_b128 v[202:205], v197 offset:1024
	ds_read_b128 v[206:209], v197 offset:2048
	ds_read_b128 v[210:213], v197 offset:3072
	ds_read_b128 v[214:217], v197 offset:4096
	ds_read_b128 v[230:233], v197 offset:5120
	ds_read_b128 v[234:237], v197 offset:6144
	ds_read_b128 v[238:241], v197 offset:7168
	global_load_lds_dwordx4 v[192:193], off
	v_lshl_add_u64 v[192:193], s[46:47], 0, v[186:187]
	s_add_i32 m0, s62, 0xe000
	s_nop 0
	global_load_lds_dwordx4 v[192:193], off
	s_waitcnt vmcnt(8)
	s_waitcnt lgkmcnt(0)
	s_barrier
	s_waitcnt lgkmcnt(0)
	v_mfma_f32_16x16x32_bf16 v[144:147], v[64:67], v[198:201], v[144:147]
	v_mfma_f32_16x16x32_bf16 v[140:143], v[152:155], v[198:201], v[140:143]
	v_mfma_f32_16x16x32_bf16 v[128:131], v[64:67], v[206:209], v[128:131]
	v_mfma_f32_16x16x32_bf16 v[124:127], v[152:155], v[206:209], v[124:127]
	v_mfma_f32_16x16x32_bf16 v[112:115], v[64:67], v[214:217], v[112:115]
	v_mfma_f32_16x16x32_bf16 v[108:111], v[152:155], v[214:217], v[108:111]
	v_mfma_f32_16x16x32_bf16 v[96:99], v[64:67], v[234:237], v[96:99]
	v_mfma_f32_16x16x32_bf16 v[92:95], v[152:155], v[234:237], v[92:95]
	v_mfma_f32_16x16x32_bf16 v[144:147], v[148:151], v[202:205], v[144:147]
	v_mfma_f32_16x16x32_bf16 v[140:143], v[156:159], v[202:205], v[140:143]
	v_mfma_f32_16x16x32_bf16 v[128:131], v[148:151], v[210:213], v[128:131]
	v_mfma_f32_16x16x32_bf16 v[124:127], v[156:159], v[210:213], v[124:127]
	v_mfma_f32_16x16x32_bf16 v[112:115], v[148:151], v[230:233], v[112:115]
	v_mfma_f32_16x16x32_bf16 v[108:111], v[156:159], v[230:233], v[108:111]
	v_mfma_f32_16x16x32_bf16 v[96:99], v[148:151], v[238:241], v[96:99]
	v_mfma_f32_16x16x32_bf16 v[92:95], v[156:159], v[238:241], v[92:95]
	v_mfma_f32_16x16x32_bf16 v[136:139], v[160:163], v[198:201], v[136:139]
	v_mfma_f32_16x16x32_bf16 v[132:135], v[168:171], v[198:201], v[132:135]
	v_mfma_f32_16x16x32_bf16 v[120:123], v[160:163], v[206:209], v[120:123]
	v_mfma_f32_16x16x32_bf16 v[116:119], v[168:171], v[206:209], v[116:119]
	v_mfma_f32_16x16x32_bf16 v[104:107], v[160:163], v[214:217], v[104:107]
	v_mfma_f32_16x16x32_bf16 v[100:103], v[168:171], v[214:217], v[100:103]
	v_mfma_f32_16x16x32_bf16 v[88:91], v[160:163], v[234:237], v[88:91]
	v_mfma_f32_16x16x32_bf16 v[84:87], v[168:171], v[234:237], v[84:87]
	v_mfma_f32_16x16x32_bf16 v[136:139], v[164:167], v[202:205], v[136:139]
	v_mfma_f32_16x16x32_bf16 v[132:135], v[188:191], v[202:205], v[132:135]
	v_mfma_f32_16x16x32_bf16 v[120:123], v[164:167], v[210:213], v[120:123]
	v_mfma_f32_16x16x32_bf16 v[116:119], v[188:191], v[210:213], v[116:119]
	v_mfma_f32_16x16x32_bf16 v[104:107], v[164:167], v[230:233], v[104:107]
	v_mfma_f32_16x16x32_bf16 v[100:103], v[188:191], v[230:233], v[100:103]
	v_mfma_f32_16x16x32_bf16 v[88:91], v[164:167], v[238:241], v[88:91]
	v_mfma_f32_16x16x32_bf16 v[84:87], v[188:191], v[238:241], v[84:87]
	s_barrier
	s_add_i32 vcc_lo, vcc_lo, s60
	v_lshl_add_u64 v[192:193], s[14:15], 0, v[172:173]
	s_mov_b32 m0, vcc_lo
	ds_read_b128 v[198:201], v197 offset:16384
	ds_read_b128 v[202:205], v197 offset:17408
	ds_read_b128 v[206:209], v197 offset:18432
	ds_read_b128 v[210:213], v197 offset:19456
	ds_read_b128 v[214:217], v197 offset:20480
	ds_read_b128 v[230:233], v197 offset:21504
	ds_read_b128 v[234:237], v197 offset:22528
	ds_read_b128 v[238:241], v197 offset:23552
	global_load_lds_dwordx4 v[192:193], off
	s_add_i32 m0, vcc_lo, 0x2000
	v_lshl_add_u64 v[242:243], s[14:15], 0, v[176:177]
	s_add_u32 s14, s14, s8
	s_addc_u32 s15, s15, 0
	s_add_i32 vcc_lo, vcc_hi, s60
	global_load_lds_dwordx4 v[242:243], off
	v_lshl_add_u64 v[244:245], s[14:15], 0, v[172:173]
	s_mov_b32 m0, vcc_lo
	v_lshl_add_u64 v[246:247], s[14:15], 0, v[176:177]
	global_load_lds_dwordx4 v[244:245], off
	s_add_i32 m0, vcc_lo, 0x2000
	v_lshl_add_u64 v[248:249], s[48:49], 0, v[0:1]
	global_load_lds_dwordx4 v[246:247], off
	s_mov_b32 m0, s62
	v_lshl_add_u64 v[226:227], s[48:49], 0, v[174:175]
	global_load_lds_dwordx4 v[248:249], off
	s_mov_b32 m0, s63
	s_nop 0
	global_load_lds_dwordx4 v[226:227], off
	s_waitcnt vmcnt(8)
	s_waitcnt lgkmcnt(0)
	s_barrier
; #define PG8_STAGE(bufoff, gbase, voff) do { _Pragma("unroll") for (int _i = 0; _i < 2; ++_i) \
;         __builtin_amdgcn_global_load_lds((const unsigned*)((const char*)(gbase) + (voff)[_i]), (PG8_LAS unsigned*)(lds + (bufoff) + ldsw + _i * 8192), 16, 0, 0); } while (0)
; #define PG8_LDA(dst, b, h) do { _Pragma("unroll") for (int m = 0; m < 4; ++m) _Pragma("unroll") for (int k = 0; k < 2; ++k) dst[m][k] = *(const PG8_LAS bf16x8*)(lds + PG8_SA(b, h) + aoff + m * 2048 + k * 1024); } while (0)
; #define PG8_LDB(dst, b, h) do { _Pragma("unroll") for (int n = 0; n < 2; ++n) _Pragma("unroll") for (int k = 0; k < 2; ++k) dst[n][k] = *(const PG8_LAS bf16x8*)(lds + PG8_SB(b, h) + boff + n * 2048 + k * 1024); } while (0)
; #define PG8_MMA(ai, bj, At, Bt) do { __builtin_amdgcn_s_setprio(1); _Pragma("unroll") for (int m = 0; m < 4; ++m) _Pragma("unroll") for (int n = 0; n < 2; ++n) _Pragma("unroll") for (int k = 0; k < 2; ++k) \
;         acc[ai][bj][m][n] = __builtin_amdgcn_mfma_f32_16x16x32_bf16(Bt[n][k], At[m][k], acc[ai][bj][m][n], 0, 0, 0); __builtin_amdgcn_s_setprio(0); } while (0)
; #define PG8_WAIT_V(n) asm volatile("s_waitcnt vmcnt(" #n ")" ::: "memory")
; #define PG8_WAIT_L(n) asm volatile("s_waitcnt lgkmcnt(" #n ")" ::: "memory")
; #define PG8_BAR __builtin_amdgcn_s_barrier()
; #define PG8_SCHED __builtin_amdgcn_sched_barrier(0)
; template <class Epi, class Sched, bool ALIGN_EPI = false, bool SP2 = false>
; __device__ __forceinline__ void gemm_phase(PG8_LAS unsigned char* lds, const Gemm g, const Sched& S, const Epi& E) {
;     ...
;             PG8_WAIT_V(8); PG8_WAIT_L(0); PG8_BAR; PG8_MMA(1, 0, At, B0); PG8_MMA(1, 1, At, B1); PG8_BAR; PG8_SCHED;
;             PG8_LDB(B0, 1, 0); PG8_LDB(B1, 1, 1); PG8_SCHED; PG8_LDA(At, 1, 0); PG8_STAGE(PG8_SA(0, 1), a2 + hstep, voffA);
;             PG8_WAIT_V(8); PG8_WAIT_L(0); PG8_BAR; PG8_MMA(0, 0, At, B0); PG8_MMA(0, 1, At, B1); PG8_BAR; PG8_SCHED;
	s_waitcnt lgkmcnt(0)
	v_mfma_f32_16x16x32_bf16 v[80:83], v[64:67], v[198:201], v[80:83]
	v_mfma_f32_16x16x32_bf16 v[76:79], v[152:155], v[198:201], v[76:79]
	v_mfma_f32_16x16x32_bf16 v[56:59], v[64:67], v[206:209], v[56:59]
	v_mfma_f32_16x16x32_bf16 v[52:55], v[152:155], v[206:209], v[52:55]
	v_mfma_f32_16x16x32_bf16 v[40:43], v[64:67], v[214:217], v[40:43]
	v_mfma_f32_16x16x32_bf16 v[36:39], v[152:155], v[214:217], v[36:39]
	v_mfma_f32_16x16x32_bf16 v[24:27], v[64:67], v[234:237], v[24:27]
	v_mfma_f32_16x16x32_bf16 v[20:23], v[152:155], v[234:237], v[20:23]
	v_mfma_f32_16x16x32_bf16 v[80:83], v[148:151], v[202:205], v[80:83]
	v_mfma_f32_16x16x32_bf16 v[76:79], v[156:159], v[202:205], v[76:79]
	v_mfma_f32_16x16x32_bf16 v[56:59], v[148:151], v[210:213], v[56:59]
	v_mfma_f32_16x16x32_bf16 v[52:55], v[156:159], v[210:213], v[52:55]
	v_mfma_f32_16x16x32_bf16 v[40:43], v[148:151], v[230:233], v[40:43]
	v_mfma_f32_16x16x32_bf16 v[36:39], v[156:159], v[230:233], v[36:39]
	v_mfma_f32_16x16x32_bf16 v[24:27], v[148:151], v[238:241], v[24:27]
	v_mfma_f32_16x16x32_bf16 v[20:23], v[156:159], v[238:241], v[20:23]
	v_mfma_f32_16x16x32_bf16 v[68:71], v[168:171], v[198:201], v[68:71]
	v_mfma_f32_16x16x32_bf16 v[48:51], v[160:163], v[206:209], v[48:51]
	v_mfma_f32_16x16x32_bf16 v[44:47], v[168:171], v[206:209], v[44:47]
	v_mfma_f32_16x16x32_bf16 v[32:35], v[160:163], v[214:217], v[32:35]
	v_mfma_f32_16x16x32_bf16 v[28:31], v[168:171], v[214:217], v[28:31]
	v_mfma_f32_16x16x32_bf16 v[16:19], v[160:163], v[234:237], v[16:19]
	v_mfma_f32_16x16x32_bf16 v[12:15], v[168:171], v[234:237], v[12:15]
	v_mfma_f32_16x16x32_bf16 v[64:67], v[160:163], v[198:201], v[72:75]
	v_mfma_f32_16x16x32_bf16 v[68:71], v[188:191], v[202:205], v[68:71]
	v_mfma_f32_16x16x32_bf16 v[48:51], v[164:167], v[210:213], v[48:51]
	v_mfma_f32_16x16x32_bf16 v[44:47], v[188:191], v[210:213], v[44:47]
	v_mfma_f32_16x16x32_bf16 v[32:35], v[164:167], v[230:233], v[32:35]
	v_mfma_f32_16x16x32_bf16 v[28:31], v[188:191], v[230:233], v[28:31]
	v_mfma_f32_16x16x32_bf16 v[16:19], v[164:167], v[238:241], v[16:19]
	v_mfma_f32_16x16x32_bf16 v[12:15], v[188:191], v[238:241], v[12:15]
	v_mfma_f32_16x16x32_bf16 v[64:67], v[164:167], v[202:205], v[64:67]
	s_barrier
	s_add_i32 vcc_lo, 0, 0x18000
	v_add_u32_e32 v3, vcc_lo, v196
	s_add_i32 vcc_hi, 0, 0x1c000
	ds_read_b128 v[72:75], v3
	ds_read_b128 v[148:151], v3 offset:1024
	ds_read_b128 v[152:155], v3 offset:2048
	ds_read_b128 v[156:159], v3 offset:3072
	v_add_u32_e32 v3, vcc_hi, v196
	ds_read_b128 v[160:163], v3
	ds_read_b128 v[164:167], v3 offset:1024
	ds_read_b128 v[168:171], v3 offset:2048
	ds_read_b128 v[188:191], v3 offset:3072
	s_add_u32 s14, s48, s8
	s_addc_u32 s15, s49, 0
	s_mov_b32 m0, s64
	v_lshl_add_u64 v[218:219], s[14:15], 0, v[0:1]
	ds_read_b128 v[198:201], v197 offset:32768
	ds_read_b128 v[202:205], v197 offset:33792
	ds_read_b128 v[206:209], v197 offset:34816
	ds_read_b128 v[210:213], v197 offset:35840
	ds_read_b128 v[214:217], v197 offset:36864
	ds_read_b128 v[230:233], v197 offset:37888
	ds_read_b128 v[234:237], v197 offset:38912
	ds_read_b128 v[238:241], v197 offset:39936
	global_load_lds_dwordx4 v[218:219], off
	v_lshl_add_u64 v[218:219], s[14:15], 0, v[174:175]
	s_mov_b32 m0, s65
	s_nop 0
	global_load_lds_dwordx4 v[218:219], off
	s_waitcnt vmcnt(8)
	s_waitcnt lgkmcnt(0)
	s_barrier
	s_waitcnt lgkmcnt(0)
	v_mfma_f32_16x16x32_bf16 v[144:147], v[72:75], v[198:201], v[144:147]
	v_mfma_f32_16x16x32_bf16 v[140:143], v[152:155], v[198:201], v[140:143]
	v_mfma_f32_16x16x32_bf16 v[128:131], v[72:75], v[206:209], v[128:131]
	v_mfma_f32_16x16x32_bf16 v[124:127], v[152:155], v[206:209], v[124:127]
	v_mfma_f32_16x16x32_bf16 v[112:115], v[72:75], v[214:217], v[112:115]
	v_mfma_f32_16x16x32_bf16 v[108:111], v[152:155], v[214:217], v[108:111]
	v_mfma_f32_16x16x32_bf16 v[96:99], v[72:75], v[234:237], v[96:99]
	v_mfma_f32_16x16x32_bf16 v[92:95], v[152:155], v[234:237], v[92:95]
	v_mfma_f32_16x16x32_bf16 v[144:147], v[148:151], v[202:205], v[144:147]
	v_mfma_f32_16x16x32_bf16 v[140:143], v[156:159], v[202:205], v[140:143]
	v_mfma_f32_16x16x32_bf16 v[128:131], v[148:151], v[210:213], v[128:131]
	v_mfma_f32_16x16x32_bf16 v[124:127], v[156:159], v[210:213], v[124:127]
	v_mfma_f32_16x16x32_bf16 v[112:115], v[148:151], v[230:233], v[112:115]
	v_mfma_f32_16x16x32_bf16 v[108:111], v[156:159], v[230:233], v[108:111]
	v_mfma_f32_16x16x32_bf16 v[96:99], v[148:151], v[238:241], v[96:99]
	v_mfma_f32_16x16x32_bf16 v[92:95], v[156:159], v[238:241], v[92:95]
	v_mfma_f32_16x16x32_bf16 v[136:139], v[160:163], v[198:201], v[136:139]
	v_mfma_f32_16x16x32_bf16 v[132:135], v[168:171], v[198:201], v[132:135]
	v_mfma_f32_16x16x32_bf16 v[120:123], v[160:163], v[206:209], v[120:123]
	v_mfma_f32_16x16x32_bf16 v[116:119], v[168:171], v[206:209], v[116:119]
	v_mfma_f32_16x16x32_bf16 v[104:107], v[160:163], v[214:217], v[104:107]
	v_mfma_f32_16x16x32_bf16 v[100:103], v[168:171], v[214:217], v[100:103]
	v_mfma_f32_16x16x32_bf16 v[88:91], v[160:163], v[234:237], v[88:91]
	v_mfma_f32_16x16x32_bf16 v[84:87], v[168:171], v[234:237], v[84:87]
	v_mfma_f32_16x16x32_bf16 v[136:139], v[164:167], v[202:205], v[136:139]
	v_mfma_f32_16x16x32_bf16 v[132:135], v[188:191], v[202:205], v[132:135]
	v_mfma_f32_16x16x32_bf16 v[120:123], v[164:167], v[210:213], v[120:123]
	v_mfma_f32_16x16x32_bf16 v[116:119], v[188:191], v[210:213], v[116:119]
	v_mfma_f32_16x16x32_bf16 v[104:107], v[164:167], v[230:233], v[104:107]
	v_mfma_f32_16x16x32_bf16 v[100:103], v[188:191], v[230:233], v[100:103]
	v_mfma_f32_16x16x32_bf16 v[88:91], v[164:167], v[238:241], v[88:91]
	v_mfma_f32_16x16x32_bf16 v[84:87], v[188:191], v[238:241], v[84:87]
	s_barrier
; #define PG8_STAGE(bufoff, gbase, voff) do { _Pragma("unroll") for (int _i = 0; _i < 2; ++_i) \
;         __builtin_amdgcn_global_load_lds((const unsigned*)((const char*)(gbase) + (voff)[_i]), (PG8_LAS unsigned*)(lds + (bufoff) + ldsw + _i * 8192), 16, 0, 0); } while (0)
; #define PG8_LDA(dst, b, h) do { _Pragma("unroll") for (int m = 0; m < 4; ++m) _Pragma("unroll") for (int k = 0; k < 2; ++k) dst[m][k] = *(const PG8_LAS bf16x8*)(lds + PG8_SA(b, h) + aoff + m * 2048 + k * 1024); } while (0)
; #define PG8_MMA(ai, bj, At, Bt) do { __builtin_amdgcn_s_setprio(1); _Pragma("unroll") for (int m = 0; m < 4; ++m) _Pragma("unroll") for (int n = 0; n < 2; ++n) _Pragma("unroll") for (int k = 0; k < 2; ++k) \
;         acc[ai][bj][m][n] = __builtin_amdgcn_mfma_f32_16x16x32_bf16(Bt[n][k], At[m][k], acc[ai][bj][m][n], 0, 0, 0); __builtin_amdgcn_s_setprio(0); } while (0)
; #define PG8_WAIT_V(n) asm volatile("s_waitcnt vmcnt(" #n ")" ::: "memory")
; #define PG8_WAIT_L(n) asm volatile("s_waitcnt lgkmcnt(" #n ")" ::: "memory")
; #define PG8_BAR __builtin_amdgcn_s_barrier()
; #define PG8_SCHED __builtin_amdgcn_sched_barrier(0)
; template <class Epi, class Sched, bool ALIGN_EPI = false, bool SP2 = false>
; __device__ __forceinline__ void gemm_phase(PG8_LAS unsigned char* lds, const Gemm g, const Sched& S, const Epi& E) {
;     ...
;         for (int t = 0; t < nt; t += 2) {
;     ...
;             PG8_LDA(At, 1, 1); PG8_STAGE(PG8_SB(1, 0), b3, voffB); PG8_STAGE(PG8_SB(1, 1), b3 + hstep, voffB); PG8_STAGE(PG8_SA(1, 0), a3, voffA);
;             PG8_WAIT_V(8); PG8_WAIT_L(0); PG8_BAR; PG8_MMA(1, 0, At, B0); PG8_MMA(1, 1, At, B1); PG8_BAR; PG8_SCHED;
	s_add_i32 s14, vcc_lo, s60
	v_lshl_add_u64 v[192:193], v[192:193], 0, s[96:97]
	s_mov_b32 m0, s14
	ds_read_b128 v[198:201], v197 offset:49152
	ds_read_b128 v[202:205], v197 offset:50176
	ds_read_b128 v[206:209], v197 offset:51200
	ds_read_b128 v[210:213], v197 offset:52224
	ds_read_b128 v[214:217], v197 offset:53248
	ds_read_b128 v[230:233], v197 offset:54272
	ds_read_b128 v[234:237], v197 offset:55296
	ds_read_b128 v[238:241], v197 offset:56320
	global_load_lds_dwordx4 v[192:193], off
	v_lshl_add_u64 v[192:193], v[242:243], 0, s[96:97]
	s_add_i32 m0, s14, 0x2000
	s_add_i32 s14, vcc_hi, s60
	global_load_lds_dwordx4 v[192:193], off
	v_lshl_add_u64 v[192:193], v[244:245], 0, s[96:97]
	s_mov_b32 m0, s14
	s_nop 0
	global_load_lds_dwordx4 v[192:193], off
	v_lshl_add_u64 v[192:193], v[246:247], 0, s[96:97]
	s_add_i32 m0, s14, 0x2000
	s_nop 0
	global_load_lds_dwordx4 v[192:193], off
	v_lshl_add_u64 v[192:193], v[248:249], 0, s[96:97]
	s_mov_b32 m0, s69
	s_nop 0
	global_load_lds_dwordx4 v[192:193], off
	v_lshl_add_u64 v[192:193], v[226:227], 0, s[96:97]
	s_mov_b32 m0, s70
	s_nop 0
	global_load_lds_dwordx4 v[192:193], off
	s_waitcnt vmcnt(8)
	s_waitcnt lgkmcnt(0)
	s_barrier
	s_waitcnt lgkmcnt(0)
	v_mfma_f32_16x16x32_bf16 v[80:83], v[72:75], v[198:201], v[80:83]
	v_mfma_f32_16x16x32_bf16 v[76:79], v[152:155], v[198:201], v[76:79]
	v_mfma_f32_16x16x32_bf16 v[56:59], v[72:75], v[206:209], v[56:59]
	v_mfma_f32_16x16x32_bf16 v[52:55], v[152:155], v[206:209], v[52:55]
	v_mfma_f32_16x16x32_bf16 v[40:43], v[72:75], v[214:217], v[40:43]
	v_mfma_f32_16x16x32_bf16 v[36:39], v[152:155], v[214:217], v[36:39]
	v_mfma_f32_16x16x32_bf16 v[24:27], v[72:75], v[234:237], v[24:27]
	v_mfma_f32_16x16x32_bf16 v[20:23], v[152:155], v[234:237], v[20:23]
	v_mfma_f32_16x16x32_bf16 v[80:83], v[148:151], v[202:205], v[80:83]
	v_mfma_f32_16x16x32_bf16 v[76:79], v[156:159], v[202:205], v[76:79]
	v_mfma_f32_16x16x32_bf16 v[56:59], v[148:151], v[210:213], v[56:59]
	v_mfma_f32_16x16x32_bf16 v[52:55], v[156:159], v[210:213], v[52:55]
	v_mfma_f32_16x16x32_bf16 v[40:43], v[148:151], v[230:233], v[40:43]
	v_mfma_f32_16x16x32_bf16 v[36:39], v[156:159], v[230:233], v[36:39]
	v_mfma_f32_16x16x32_bf16 v[24:27], v[148:151], v[238:241], v[24:27]
	v_mfma_f32_16x16x32_bf16 v[20:23], v[156:159], v[238:241], v[20:23]
	v_mfma_f32_16x16x32_bf16 v[64:67], v[160:163], v[198:201], v[64:67]
	v_mfma_f32_16x16x32_bf16 v[72:75], v[164:167], v[202:205], v[64:67]
	v_mfma_f32_16x16x32_bf16 v[64:67], v[168:171], v[198:201], v[68:71]
	v_mfma_f32_16x16x32_bf16 v[48:51], v[160:163], v[206:209], v[48:51]
	v_mfma_f32_16x16x32_bf16 v[44:47], v[168:171], v[206:209], v[44:47]
	v_mfma_f32_16x16x32_bf16 v[32:35], v[160:163], v[214:217], v[32:35]
	v_mfma_f32_16x16x32_bf16 v[28:31], v[168:171], v[214:217], v[28:31]
	v_mfma_f32_16x16x32_bf16 v[16:19], v[160:163], v[234:237], v[16:19]
	v_mfma_f32_16x16x32_bf16 v[12:15], v[168:171], v[234:237], v[12:15]
	v_mfma_f32_16x16x32_bf16 v[68:71], v[188:191], v[202:205], v[64:67]
	v_mfma_f32_16x16x32_bf16 v[48:51], v[164:167], v[210:213], v[48:51]
	v_mfma_f32_16x16x32_bf16 v[44:47], v[188:191], v[210:213], v[44:47]
	v_mfma_f32_16x16x32_bf16 v[32:35], v[164:167], v[230:233], v[32:35]
	v_mfma_f32_16x16x32_bf16 v[28:31], v[188:191], v[230:233], v[28:31]
	v_mfma_f32_16x16x32_bf16 v[16:19], v[164:167], v[238:241], v[16:19]
	v_mfma_f32_16x16x32_bf16 v[12:15], v[188:191], v[238:241], v[12:15]
	s_barrier
	s_add_u32 s46, s46, 0x100
	s_addc_u32 s47, s47, 0
	s_add_u32 s3, s3, 0x100
	s_addc_u32 s83, s83, 0
	s_cmp_ge_u32 s81, s66
	s_cbranch_scc1 .LBB0_72

; #define PG8_STAGE(bufoff, gbase, voff) do { _Pragma("unroll") for (int _i = 0; _i < 2; ++_i) \
;         __builtin_amdgcn_global_load_lds((const unsigned*)((const char*)(gbase) + (voff)[_i]), (PG8_LAS unsigned*)(lds + (bufoff) + ldsw + _i * 8192), 16, 0, 0); } while (0)
; #define PG8_LDA(dst, b, h) do { _Pragma("unroll") for (int m = 0; m < 4; ++m) _Pragma("unroll") for (int k = 0; k < 2; ++k) dst[m][k] = *(const PG8_LAS bf16x8*)(lds + PG8_SA(b, h) + aoff + m * 2048 + k * 1024); } while (0)
; #define PG8_LDB(dst, b, h) do { _Pragma("unroll") for (int n = 0; n < 2; ++n) _Pragma("unroll") for (int k = 0; k < 2; ++k) dst[n][k] = *(const PG8_LAS bf16x8*)(lds + PG8_SB(b, h) + boff + n * 2048 + k * 1024); } while (0)
; #define PG8_MMA(ai, bj, At, Bt) do { __builtin_amdgcn_s_setprio(1); _Pragma("unroll") for (int m = 0; m < 4; ++m) _Pragma("unroll") for (int n = 0; n < 2; ++n) _Pragma("unroll") for (int k = 0; k < 2; ++k) \
;         acc[ai][bj][m][n] = __builtin_amdgcn_mfma_f32_16x16x32_bf16(Bt[n][k], At[m][k], acc[ai][bj][m][n], 0, 0, 0); __builtin_amdgcn_s_setprio(0); } while (0)
; #define PG8_WAIT_V(n) asm volatile("s_waitcnt vmcnt(" #n ")" ::: "memory")
; #define PG8_WAIT_L(n) asm volatile("s_waitcnt lgkmcnt(" #n ")" ::: "memory")
; #define PG8_BAR __builtin_amdgcn_s_barrier()
; #define PG8_SCHED __builtin_amdgcn_sched_barrier(0)
; template <class Epi, class Sched, bool ALIGN_EPI = false, bool SP2 = false>
; __device__ __forceinline__ void gemm_phase(PG8_LAS unsigned char* lds, const Gemm g, const Sched& S, const Epi& E) {
;     ...
;             PG8_LDB(B0, 0, 0); PG8_LDB(B1, 0, 1); PG8_SCHED; PG8_LDA(At, 0, 0); PG8_STAGE(PG8_SA(1, 1), a1 + hstep, voffA);
;             PG8_WAIT_V(8); PG8_WAIT_L(0); PG8_BAR; PG8_MMA(0, 0, At, B0); PG8_MMA(0, 1, At, B1); PG8_BAR; PG8_SCHED;
;             PG8_LDA(At, 0, 1); PG8_STAGE(PG8_SB(0, 0), b2, voffB); PG8_STAGE(PG8_SB(0, 1), b2 + hstep, voffB); PG8_STAGE(PG8_SA(0, 0), a2, voffA);
;             PG8_WAIT_V(8); PG8_WAIT_L(0); PG8_BAR; PG8_MMA(1, 0, At, B0); PG8_MMA(1, 1, At, B1); PG8_BAR; PG8_SCHED;
.LBB0_454:
	s_add_u32 s26, s2, 0xfffc0080
	s_addc_u32 s27, s3, -1
	s_and_b64 s[24:25], s[24:25], exec
	s_cselect_b32 s27, s17, s27
	s_cselect_b32 s26, s46, s26
	s_cselect_b32 s25, s15, s50
	s_cselect_b32 s24, s47, s49
	s_add_i32 s52, 0, 0x10000
	s_add_i32 s54, 0, 0x14000
	v_add_u32_e32 v136, s52, v181
	v_add_u32_e32 v180, s54, v181
	ds_read_b128 v[124:127], v136
	ds_read_b128 v[128:131], v136 offset:1024
	ds_read_b128 v[132:135], v136 offset:2048
	ds_read_b128 v[136:139], v136 offset:3072
	ds_read_b128 v[140:143], v180
	ds_read_b128 v[144:147], v180 offset:1024
	ds_read_b128 v[148:151], v180 offset:2048
	ds_read_b128 v[182:185], v180 offset:3072
	v_lshl_add_u64 v[186:187], s[2:3], 0, v[176:177]
	s_add_i32 m0, s23, 0xc000
	ds_read_b128 v[198:201], v197
	ds_read_b128 v[202:205], v197 offset:1024
	ds_read_b128 v[206:209], v197 offset:2048
	ds_read_b128 v[210:213], v197 offset:3072
	ds_read_b128 v[214:217], v197 offset:4096
	ds_read_b128 v[230:233], v197 offset:5120
	ds_read_b128 v[234:237], v197 offset:6144
	ds_read_b128 v[238:241], v197 offset:7168
	global_load_lds_dwordx4 v[186:187], off
	v_lshl_add_u64 v[186:187], s[2:3], 0, v[178:179]
	s_add_i32 m0, s23, 0xe000
	s_nop 0
	global_load_lds_dwordx4 v[186:187], off
	s_waitcnt vmcnt(8)
	s_waitcnt lgkmcnt(0)
	s_barrier
	s_waitcnt lgkmcnt(0)
	v_mfma_f32_16x16x32_bf16 v[160:163], v[124:127], v[198:201], v[160:163]
	v_mfma_f32_16x16x32_bf16 v[156:159], v[132:135], v[198:201], v[156:159]
	v_mfma_f32_16x16x32_bf16 v[112:115], v[124:127], v[206:209], v[112:115]
	v_mfma_f32_16x16x32_bf16 v[108:111], v[132:135], v[206:209], v[108:111]
	v_mfma_f32_16x16x32_bf16 v[96:99], v[124:127], v[214:217], v[96:99]
	v_mfma_f32_16x16x32_bf16 v[92:95], v[132:135], v[214:217], v[92:95]
	v_mfma_f32_16x16x32_bf16 v[80:83], v[124:127], v[234:237], v[80:83]
	v_mfma_f32_16x16x32_bf16 v[76:79], v[132:135], v[234:237], v[76:79]
	v_mfma_f32_16x16x32_bf16 v[160:163], v[128:131], v[202:205], v[160:163]
	v_mfma_f32_16x16x32_bf16 v[156:159], v[136:139], v[202:205], v[156:159]
	v_mfma_f32_16x16x32_bf16 v[112:115], v[128:131], v[210:213], v[112:115]
	v_mfma_f32_16x16x32_bf16 v[108:111], v[136:139], v[210:213], v[108:111]
	v_mfma_f32_16x16x32_bf16 v[96:99], v[128:131], v[230:233], v[96:99]
	v_mfma_f32_16x16x32_bf16 v[92:95], v[136:139], v[230:233], v[92:95]
	v_mfma_f32_16x16x32_bf16 v[80:83], v[128:131], v[238:241], v[80:83]
	v_mfma_f32_16x16x32_bf16 v[76:79], v[136:139], v[238:241], v[76:79]
	v_mfma_f32_16x16x32_bf16 v[152:155], v[140:143], v[198:201], v[152:155]
	v_mfma_f32_16x16x32_bf16 v[120:123], v[148:151], v[198:201], v[120:123]
	v_mfma_f32_16x16x32_bf16 v[104:107], v[140:143], v[206:209], v[104:107]
	v_mfma_f32_16x16x32_bf16 v[100:103], v[148:151], v[206:209], v[100:103]
	v_mfma_f32_16x16x32_bf16 v[88:91], v[140:143], v[214:217], v[88:91]
	v_mfma_f32_16x16x32_bf16 v[84:87], v[148:151], v[214:217], v[84:87]
	v_mfma_f32_16x16x32_bf16 v[72:75], v[140:143], v[234:237], v[72:75]
	v_mfma_f32_16x16x32_bf16 v[68:71], v[148:151], v[234:237], v[68:71]
	v_mfma_f32_16x16x32_bf16 v[152:155], v[144:147], v[202:205], v[152:155]
	v_mfma_f32_16x16x32_bf16 v[120:123], v[182:185], v[202:205], v[120:123]
	v_mfma_f32_16x16x32_bf16 v[104:107], v[144:147], v[210:213], v[104:107]
	v_mfma_f32_16x16x32_bf16 v[100:103], v[182:185], v[210:213], v[100:103]
	v_mfma_f32_16x16x32_bf16 v[88:91], v[144:147], v[230:233], v[88:91]
	v_mfma_f32_16x16x32_bf16 v[84:87], v[182:185], v[230:233], v[84:87]
	v_mfma_f32_16x16x32_bf16 v[72:75], v[144:147], v[238:241], v[72:75]
	v_mfma_f32_16x16x32_bf16 v[68:71], v[182:185], v[238:241], v[68:71]
	s_barrier
	s_add_i32 s52, s52, s13
	v_lshl_add_u64 v[186:187], s[24:25], 0, v[166:167]
	s_mov_b32 m0, s52
	ds_read_b128 v[198:201], v197 offset:16384
	ds_read_b128 v[202:205], v197 offset:17408
	ds_read_b128 v[206:209], v197 offset:18432
	ds_read_b128 v[210:213], v197 offset:19456
	ds_read_b128 v[214:217], v197 offset:20480
	ds_read_b128 v[230:233], v197 offset:21504
	ds_read_b128 v[234:237], v197 offset:22528
	ds_read_b128 v[238:241], v197 offset:23552
	global_load_lds_dwordx4 v[186:187], off
	s_add_i32 m0, s52, 0x2000
	s_add_u32 s52, s24, 0x40000
	v_lshl_add_u64 v[190:191], s[24:25], 0, v[0:1]
	s_addc_u32 s53, s25, 0
	s_add_i32 s54, s54, s13
	global_load_lds_dwordx4 v[190:191], off
	v_lshl_add_u64 v[194:195], s[52:53], 0, v[166:167]
	s_mov_b32 m0, s54
	v_lshl_add_u64 v[218:219], s[26:27], 0, v[164:165]
	global_load_lds_dwordx4 v[194:195], off
	v_lshl_add_u64 v[194:195], s[52:53], 0, v[0:1]
	s_add_i32 m0, s54, 0x2000
	s_nop 0
	global_load_lds_dwordx4 v[194:195], off
	v_lshl_add_u64 v[194:195], s[26:27], 0, v[168:169]
	s_mov_b32 m0, s23
	s_nop 0
	global_load_lds_dwordx4 v[194:195], off
	s_mov_b32 m0, s34
	s_nop 0
	global_load_lds_dwordx4 v[218:219], off
	s_waitcnt vmcnt(8)
	s_waitcnt lgkmcnt(0)
	s_barrier
; #define PG8_STAGE(bufoff, gbase, voff) do { _Pragma("unroll") for (int _i = 0; _i < 2; ++_i) \
;         __builtin_amdgcn_global_load_lds((const unsigned*)((const char*)(gbase) + (voff)[_i]), (PG8_LAS unsigned*)(lds + (bufoff) + ldsw + _i * 8192), 16, 0, 0); } while (0)
; #define PG8_LDA(dst, b, h) do { _Pragma("unroll") for (int m = 0; m < 4; ++m) _Pragma("unroll") for (int k = 0; k < 2; ++k) dst[m][k] = *(const PG8_LAS bf16x8*)(lds + PG8_SA(b, h) + aoff + m * 2048 + k * 1024); } while (0)
; #define PG8_LDB(dst, b, h) do { _Pragma("unroll") for (int n = 0; n < 2; ++n) _Pragma("unroll") for (int k = 0; k < 2; ++k) dst[n][k] = *(const PG8_LAS bf16x8*)(lds + PG8_SB(b, h) + boff + n * 2048 + k * 1024); } while (0)
; #define PG8_MMA(ai, bj, At, Bt) do { __builtin_amdgcn_s_setprio(1); _Pragma("unroll") for (int m = 0; m < 4; ++m) _Pragma("unroll") for (int n = 0; n < 2; ++n) _Pragma("unroll") for (int k = 0; k < 2; ++k) \
;         acc[ai][bj][m][n] = __builtin_amdgcn_mfma_f32_16x16x32_bf16(Bt[n][k], At[m][k], acc[ai][bj][m][n], 0, 0, 0); __builtin_amdgcn_s_setprio(0); } while (0)
; #define PG8_WAIT_V(n) asm volatile("s_waitcnt vmcnt(" #n ")" ::: "memory")
; #define PG8_WAIT_L(n) asm volatile("s_waitcnt lgkmcnt(" #n ")" ::: "memory")
; #define PG8_BAR __builtin_amdgcn_s_barrier()
; #define PG8_SCHED __builtin_amdgcn_sched_barrier(0)
; template <class Epi, class Sched, bool ALIGN_EPI = false, bool SP2 = false>
; __device__ __forceinline__ void gemm_phase(PG8_LAS unsigned char* lds, const Gemm g, const Sched& S, const Epi& E) {
;     ...
;             PG8_WAIT_V(8); PG8_WAIT_L(0); PG8_BAR; PG8_MMA(1, 0, At, B0); PG8_MMA(1, 1, At, B1); PG8_BAR; PG8_SCHED;
;             PG8_LDB(B0, 1, 0); PG8_LDB(B1, 1, 1); PG8_SCHED; PG8_LDA(At, 1, 0); PG8_STAGE(PG8_SA(0, 1), a2 + hstep, voffA);
;             PG8_WAIT_V(8); PG8_WAIT_L(0); PG8_BAR; PG8_MMA(0, 0, At, B0); PG8_MMA(0, 1, At, B1); PG8_BAR; PG8_SCHED;
	s_waitcnt lgkmcnt(0)
	v_mfma_f32_16x16x32_bf16 v[64:67], v[124:127], v[198:201], v[64:67]
	v_mfma_f32_16x16x32_bf16 v[60:63], v[132:135], v[198:201], v[60:63]
	v_mfma_f32_16x16x32_bf16 v[48:51], v[124:127], v[206:209], v[48:51]
	v_mfma_f32_16x16x32_bf16 v[44:47], v[132:135], v[206:209], v[44:47]
	v_mfma_f32_16x16x32_bf16 v[32:35], v[124:127], v[214:217], v[32:35]
	v_mfma_f32_16x16x32_bf16 v[28:31], v[132:135], v[214:217], v[28:31]
	v_mfma_f32_16x16x32_bf16 v[16:19], v[124:127], v[234:237], v[16:19]
	v_mfma_f32_16x16x32_bf16 v[12:15], v[132:135], v[234:237], v[12:15]
	v_mfma_f32_16x16x32_bf16 v[64:67], v[128:131], v[202:205], v[64:67]
	v_mfma_f32_16x16x32_bf16 v[60:63], v[136:139], v[202:205], v[60:63]
	v_mfma_f32_16x16x32_bf16 v[48:51], v[128:131], v[210:213], v[48:51]
	v_mfma_f32_16x16x32_bf16 v[44:47], v[136:139], v[210:213], v[44:47]
	v_mfma_f32_16x16x32_bf16 v[32:35], v[128:131], v[230:233], v[32:35]
	v_mfma_f32_16x16x32_bf16 v[28:31], v[136:139], v[230:233], v[28:31]
	v_mfma_f32_16x16x32_bf16 v[16:19], v[128:131], v[238:241], v[16:19]
	v_mfma_f32_16x16x32_bf16 v[12:15], v[136:139], v[238:241], v[12:15]
	v_mfma_f32_16x16x32_bf16 v[56:59], v[140:143], v[198:201], v[56:59]
	v_mfma_f32_16x16x32_bf16 v[52:55], v[148:151], v[198:201], v[52:55]
	v_mfma_f32_16x16x32_bf16 v[40:43], v[140:143], v[206:209], v[40:43]
	v_mfma_f32_16x16x32_bf16 v[36:39], v[148:151], v[206:209], v[36:39]
	v_mfma_f32_16x16x32_bf16 v[24:27], v[140:143], v[214:217], v[24:27]
	v_mfma_f32_16x16x32_bf16 v[20:23], v[148:151], v[214:217], v[20:23]
	v_mfma_f32_16x16x32_bf16 v[8:11], v[140:143], v[234:237], v[8:11]
	v_mfma_f32_16x16x32_bf16 v[4:7], v[148:151], v[234:237], v[4:7]
	v_mfma_f32_16x16x32_bf16 v[56:59], v[144:147], v[202:205], v[56:59]
	v_mfma_f32_16x16x32_bf16 v[52:55], v[182:185], v[202:205], v[52:55]
	v_mfma_f32_16x16x32_bf16 v[40:43], v[144:147], v[210:213], v[40:43]
	v_mfma_f32_16x16x32_bf16 v[36:39], v[182:185], v[210:213], v[36:39]
	v_mfma_f32_16x16x32_bf16 v[24:27], v[144:147], v[230:233], v[24:27]
	v_mfma_f32_16x16x32_bf16 v[20:23], v[182:185], v[230:233], v[20:23]
	v_mfma_f32_16x16x32_bf16 v[8:11], v[144:147], v[238:241], v[8:11]
	v_mfma_f32_16x16x32_bf16 v[4:7], v[182:185], v[238:241], v[4:7]
	s_barrier
	s_add_i32 s52, 0, 0x18000
	s_add_i32 s53, 0, 0x1c000
	v_add_u32_e32 v136, s52, v181
	v_add_u32_e32 v180, s53, v181
	ds_read_b128 v[124:127], v136
	ds_read_b128 v[128:131], v136 offset:1024
	ds_read_b128 v[132:135], v136 offset:2048
	ds_read_b128 v[136:139], v136 offset:3072
	ds_read_b128 v[140:143], v180
	ds_read_b128 v[144:147], v180 offset:1024
	ds_read_b128 v[148:151], v180 offset:2048
	ds_read_b128 v[182:185], v180 offset:3072
	s_add_u32 s26, s26, 0x40000
	s_addc_u32 s27, s27, 0
	s_mov_b32 m0, s35
	v_lshl_add_u64 v[226:227], s[26:27], 0, v[168:169]
	ds_read_b128 v[198:201], v197 offset:32768
	ds_read_b128 v[202:205], v197 offset:33792
	ds_read_b128 v[206:209], v197 offset:34816
	ds_read_b128 v[210:213], v197 offset:35840
	ds_read_b128 v[214:217], v197 offset:36864
	ds_read_b128 v[230:233], v197 offset:37888
	ds_read_b128 v[234:237], v197 offset:38912
	ds_read_b128 v[238:241], v197 offset:39936
	global_load_lds_dwordx4 v[226:227], off
	v_lshl_add_u64 v[226:227], s[26:27], 0, v[164:165]
	s_mov_b32 m0, s36
	s_nop 0
	global_load_lds_dwordx4 v[226:227], off
	s_waitcnt vmcnt(8)
	s_waitcnt lgkmcnt(0)
	s_barrier
	s_waitcnt lgkmcnt(0)
	v_mfma_f32_16x16x32_bf16 v[160:163], v[124:127], v[198:201], v[160:163]
	v_mfma_f32_16x16x32_bf16 v[156:159], v[132:135], v[198:201], v[156:159]
	v_mfma_f32_16x16x32_bf16 v[112:115], v[124:127], v[206:209], v[112:115]
	v_mfma_f32_16x16x32_bf16 v[108:111], v[132:135], v[206:209], v[108:111]
	v_mfma_f32_16x16x32_bf16 v[96:99], v[124:127], v[214:217], v[96:99]
	v_mfma_f32_16x16x32_bf16 v[92:95], v[132:135], v[214:217], v[92:95]
	v_mfma_f32_16x16x32_bf16 v[80:83], v[124:127], v[234:237], v[80:83]
	v_mfma_f32_16x16x32_bf16 v[76:79], v[132:135], v[234:237], v[76:79]
	v_mfma_f32_16x16x32_bf16 v[160:163], v[128:131], v[202:205], v[160:163]
	v_mfma_f32_16x16x32_bf16 v[156:159], v[136:139], v[202:205], v[156:159]
	v_mfma_f32_16x16x32_bf16 v[112:115], v[128:131], v[210:213], v[112:115]
	v_mfma_f32_16x16x32_bf16 v[108:111], v[136:139], v[210:213], v[108:111]
	v_mfma_f32_16x16x32_bf16 v[96:99], v[128:131], v[230:233], v[96:99]
	v_mfma_f32_16x16x32_bf16 v[92:95], v[136:139], v[230:233], v[92:95]
	v_mfma_f32_16x16x32_bf16 v[80:83], v[128:131], v[238:241], v[80:83]
	v_mfma_f32_16x16x32_bf16 v[76:79], v[136:139], v[238:241], v[76:79]
	v_mfma_f32_16x16x32_bf16 v[152:155], v[140:143], v[198:201], v[152:155]
	v_mfma_f32_16x16x32_bf16 v[120:123], v[148:151], v[198:201], v[120:123]
	v_mfma_f32_16x16x32_bf16 v[104:107], v[140:143], v[206:209], v[104:107]
	v_mfma_f32_16x16x32_bf16 v[100:103], v[148:151], v[206:209], v[100:103]
	v_mfma_f32_16x16x32_bf16 v[88:91], v[140:143], v[214:217], v[88:91]
	v_mfma_f32_16x16x32_bf16 v[84:87], v[148:151], v[214:217], v[84:87]
	v_mfma_f32_16x16x32_bf16 v[72:75], v[140:143], v[234:237], v[72:75]
	v_mfma_f32_16x16x32_bf16 v[68:71], v[148:151], v[234:237], v[68:71]
	v_mfma_f32_16x16x32_bf16 v[152:155], v[144:147], v[202:205], v[152:155]
	v_mfma_f32_16x16x32_bf16 v[120:123], v[182:185], v[202:205], v[120:123]
	v_mfma_f32_16x16x32_bf16 v[104:107], v[144:147], v[210:213], v[104:107]
	v_mfma_f32_16x16x32_bf16 v[100:103], v[182:185], v[210:213], v[100:103]
	v_mfma_f32_16x16x32_bf16 v[88:91], v[144:147], v[230:233], v[88:91]
	v_mfma_f32_16x16x32_bf16 v[84:87], v[182:185], v[230:233], v[84:87]
	v_mfma_f32_16x16x32_bf16 v[72:75], v[144:147], v[238:241], v[72:75]
	v_mfma_f32_16x16x32_bf16 v[68:71], v[182:185], v[238:241], v[68:71]
	s_barrier
; #define PG8_STAGE(bufoff, gbase, voff) do { _Pragma("unroll") for (int _i = 0; _i < 2; ++_i) \
;         __builtin_amdgcn_global_load_lds((const unsigned*)((const char*)(gbase) + (voff)[_i]), (PG8_LAS unsigned*)(lds + (bufoff) + ldsw + _i * 8192), 16, 0, 0); } while (0)
; #define PG8_LDA(dst, b, h) do { _Pragma("unroll") for (int m = 0; m < 4; ++m) _Pragma("unroll") for (int k = 0; k < 2; ++k) dst[m][k] = *(const PG8_LAS bf16x8*)(lds + PG8_SA(b, h) + aoff + m * 2048 + k * 1024); } while (0)
; #define PG8_MMA(ai, bj, At, Bt) do { __builtin_amdgcn_s_setprio(1); _Pragma("unroll") for (int m = 0; m < 4; ++m) _Pragma("unroll") for (int n = 0; n < 2; ++n) _Pragma("unroll") for (int k = 0; k < 2; ++k) \
;         acc[ai][bj][m][n] = __builtin_amdgcn_mfma_f32_16x16x32_bf16(Bt[n][k], At[m][k], acc[ai][bj][m][n], 0, 0, 0); __builtin_amdgcn_s_setprio(0); } while (0)
; #define PG8_WAIT_V(n) asm volatile("s_waitcnt vmcnt(" #n ")" ::: "memory")
; #define PG8_WAIT_L(n) asm volatile("s_waitcnt lgkmcnt(" #n ")" ::: "memory")
; #define PG8_BAR __builtin_amdgcn_s_barrier()
; #define PG8_SCHED __builtin_amdgcn_sched_barrier(0)
; template <class Epi, class Sched, bool ALIGN_EPI = false, bool SP2 = false>
; __device__ __forceinline__ void gemm_phase(PG8_LAS unsigned char* lds, const Gemm g, const Sched& S, const Epi& E) {
;     ...
;         for (int t = 0; t < nt; t += 2) {
;     ...
;             PG8_LDA(At, 1, 1); PG8_STAGE(PG8_SB(1, 0), b3, voffB); PG8_STAGE(PG8_SB(1, 1), b3 + hstep, voffB); PG8_STAGE(PG8_SA(1, 0), a3, voffA);
;             PG8_WAIT_V(8); PG8_WAIT_L(0); PG8_BAR; PG8_MMA(1, 0, At, B0); PG8_MMA(1, 1, At, B1); PG8_BAR; PG8_SCHED;
	s_add_i32 s26, s52, s13
	v_lshl_add_u64 v[186:187], v[186:187], 0, s[96:97]
	s_mov_b32 m0, s26
	ds_read_b128 v[198:201], v197 offset:49152
	ds_read_b128 v[202:205], v197 offset:50176
	ds_read_b128 v[206:209], v197 offset:51200
	ds_read_b128 v[210:213], v197 offset:52224
	ds_read_b128 v[214:217], v197 offset:53248
	ds_read_b128 v[230:233], v197 offset:54272
	ds_read_b128 v[234:237], v197 offset:55296
	ds_read_b128 v[238:241], v197 offset:56320
	global_load_lds_dwordx4 v[186:187], off
	s_add_i32 m0, s26, 0x2000
	s_add_u32 s24, s24, 0x40080
	v_lshl_add_u64 v[186:187], v[190:191], 0, s[96:97]
	s_addc_u32 s25, s25, 0
	s_add_i32 s26, s53, s13
	global_load_lds_dwordx4 v[186:187], off
	v_lshl_add_u64 v[186:187], s[24:25], 0, v[166:167]
	s_mov_b32 m0, s26
	s_nop 0
	global_load_lds_dwordx4 v[186:187], off
	v_lshl_add_u64 v[186:187], s[24:25], 0, v[0:1]
	s_add_i32 m0, s26, 0x2000
	s_nop 0
	global_load_lds_dwordx4 v[186:187], off
	v_lshl_add_u64 v[186:187], v[194:195], 0, s[96:97]
	s_mov_b32 m0, s37
	s_nop 0
	global_load_lds_dwordx4 v[186:187], off
	v_lshl_add_u64 v[186:187], v[218:219], 0, s[96:97]
	s_mov_b32 m0, s42
	s_nop 0
	global_load_lds_dwordx4 v[186:187], off
	s_waitcnt vmcnt(8)
	s_waitcnt lgkmcnt(0)
	s_barrier
	s_waitcnt lgkmcnt(0)
	v_mfma_f32_16x16x32_bf16 v[64:67], v[124:127], v[198:201], v[64:67]
	v_mfma_f32_16x16x32_bf16 v[60:63], v[132:135], v[198:201], v[60:63]
	v_mfma_f32_16x16x32_bf16 v[48:51], v[124:127], v[206:209], v[48:51]
	v_mfma_f32_16x16x32_bf16 v[44:47], v[132:135], v[206:209], v[44:47]
	v_mfma_f32_16x16x32_bf16 v[32:35], v[124:127], v[214:217], v[32:35]
	v_mfma_f32_16x16x32_bf16 v[28:31], v[132:135], v[214:217], v[28:31]
	v_mfma_f32_16x16x32_bf16 v[16:19], v[124:127], v[234:237], v[16:19]
	v_mfma_f32_16x16x32_bf16 v[12:15], v[132:135], v[234:237], v[12:15]
	v_mfma_f32_16x16x32_bf16 v[64:67], v[128:131], v[202:205], v[64:67]
	v_mfma_f32_16x16x32_bf16 v[60:63], v[136:139], v[202:205], v[60:63]
	v_mfma_f32_16x16x32_bf16 v[48:51], v[128:131], v[210:213], v[48:51]
	v_mfma_f32_16x16x32_bf16 v[44:47], v[136:139], v[210:213], v[44:47]
	v_mfma_f32_16x16x32_bf16 v[32:35], v[128:131], v[230:233], v[32:35]
	v_mfma_f32_16x16x32_bf16 v[28:31], v[136:139], v[230:233], v[28:31]
	v_mfma_f32_16x16x32_bf16 v[16:19], v[128:131], v[238:241], v[16:19]
	v_mfma_f32_16x16x32_bf16 v[12:15], v[136:139], v[238:241], v[12:15]
	v_mfma_f32_16x16x32_bf16 v[56:59], v[140:143], v[198:201], v[56:59]
	v_mfma_f32_16x16x32_bf16 v[52:55], v[148:151], v[198:201], v[52:55]
	v_mfma_f32_16x16x32_bf16 v[40:43], v[140:143], v[206:209], v[40:43]
	v_mfma_f32_16x16x32_bf16 v[36:39], v[148:151], v[206:209], v[36:39]
	v_mfma_f32_16x16x32_bf16 v[24:27], v[140:143], v[214:217], v[24:27]
	v_mfma_f32_16x16x32_bf16 v[20:23], v[148:151], v[214:217], v[20:23]
	v_mfma_f32_16x16x32_bf16 v[8:11], v[140:143], v[234:237], v[8:11]
	v_mfma_f32_16x16x32_bf16 v[4:7], v[148:151], v[234:237], v[4:7]
	v_mfma_f32_16x16x32_bf16 v[56:59], v[144:147], v[202:205], v[56:59]
	v_mfma_f32_16x16x32_bf16 v[52:55], v[182:185], v[202:205], v[52:55]
	v_mfma_f32_16x16x32_bf16 v[40:43], v[144:147], v[210:213], v[40:43]
	v_mfma_f32_16x16x32_bf16 v[36:39], v[182:185], v[210:213], v[36:39]
	v_mfma_f32_16x16x32_bf16 v[24:27], v[144:147], v[230:233], v[24:27]
	v_mfma_f32_16x16x32_bf16 v[20:23], v[182:185], v[230:233], v[20:23]
	v_mfma_f32_16x16x32_bf16 v[8:11], v[144:147], v[238:241], v[8:11]
	v_mfma_f32_16x16x32_bf16 v[4:7], v[182:185], v[238:241], v[4:7]
	s_barrier
	s_add_i32 s51, s51, 2
	s_add_u32 s2, s2, 0x100
	s_addc_u32 s3, s3, 0
	s_add_u32 s49, s49, 0x100
	s_addc_u32 s50, s50, 0
	s_cmp_gt_u32 s51, 13
	s_cbranch_scc1 .LBB0_457

; #define PG8_STAGE(bufoff, gbase, voff) do { _Pragma("unroll") for (int _i = 0; _i < 2; ++_i) \
;         __builtin_amdgcn_global_load_lds((const unsigned*)((const char*)(gbase) + (voff)[_i]), (PG8_LAS unsigned*)(lds + (bufoff) + ldsw + _i * 8192), 16, 0, 0); } while (0)
; #define PG8_LDA(dst, b, h) do { _Pragma("unroll") for (int m = 0; m < 4; ++m) _Pragma("unroll") for (int k = 0; k < 2; ++k) dst[m][k] = *(const PG8_LAS bf16x8*)(lds + PG8_SA(b, h) + aoff + m * 2048 + k * 1024); } while (0)
; #define PG8_LDB(dst, b, h) do { _Pragma("unroll") for (int n = 0; n < 2; ++n) _Pragma("unroll") for (int k = 0; k < 2; ++k) dst[n][k] = *(const PG8_LAS bf16x8*)(lds + PG8_SB(b, h) + boff + n * 2048 + k * 1024); } while (0)
; #define PG8_MMA(ai, bj, At, Bt) do { __builtin_amdgcn_s_setprio(1); _Pragma("unroll") for (int m = 0; m < 4; ++m) _Pragma("unroll") for (int n = 0; n < 2; ++n) _Pragma("unroll") for (int k = 0; k < 2; ++k) \
;         acc[ai][bj][m][n] = __builtin_amdgcn_mfma_f32_16x16x32_bf16(Bt[n][k], At[m][k], acc[ai][bj][m][n], 0, 0, 0); __builtin_amdgcn_s_setprio(0); } while (0)
; #define PG8_WAIT_V(n) asm volatile("s_waitcnt vmcnt(" #n ")" ::: "memory")
; #define PG8_WAIT_L(n) asm volatile("s_waitcnt lgkmcnt(" #n ")" ::: "memory")
; #define PG8_BAR __builtin_amdgcn_s_barrier()
; #define PG8_SCHED __builtin_amdgcn_sched_barrier(0)
; template <class Epi, class Sched, bool ALIGN_EPI = false, bool SP2 = false>
; __device__ __forceinline__ void gemm_phase(PG8_LAS unsigned char* lds, const Gemm g, const Sched& S, const Epi& E) {
;     ...
;             PG8_LDB(B0, 0, 0); PG8_LDB(B1, 0, 1); PG8_SCHED; PG8_LDA(At, 0, 0); PG8_STAGE(PG8_SA(1, 1), a1 + hstep, voffA);
;             PG8_WAIT_V(8); PG8_WAIT_L(0); PG8_BAR; PG8_MMA(0, 0, At, B0); PG8_MMA(0, 1, At, B1); PG8_BAR; PG8_SCHED;
;             PG8_LDA(At, 0, 1); PG8_STAGE(PG8_SB(0, 0), b2, voffB); PG8_STAGE(PG8_SB(0, 1), b2 + hstep, voffB); PG8_STAGE(PG8_SA(0, 0), a2, voffA);
;             PG8_WAIT_V(8); PG8_WAIT_L(0); PG8_BAR; PG8_MMA(1, 0, At, B0); PG8_MMA(1, 1, At, B1); PG8_BAR; PG8_SCHED;
.LBB0_512:
	s_add_u32 s34, s2, 0xfffc0080
	s_addc_u32 s35, s3, -1
	s_and_b64 s[30:31], s[30:31], exec
	s_cselect_b32 s35, s35, s23
	s_cselect_b32 s34, s34, s57
	s_cselect_b32 s31, s61, s21
	s_cselect_b32 s30, s60, s58
	s_add_i32 s64, 0, 0x10000
	s_add_i32 s66, 0, 0x14000
	v_add_u32_e32 v148, s64, v181
	v_add_u32_e32 v180, s66, v181
	ds_read_b128 v[136:139], v148
	ds_read_b128 v[140:143], v148 offset:1024
	ds_read_b128 v[144:147], v148 offset:2048
	ds_read_b128 v[148:151], v148 offset:3072
	ds_read_b128 v[152:155], v180
	ds_read_b128 v[156:159], v180 offset:1024
	ds_read_b128 v[160:163], v180 offset:2048
	ds_read_b128 v[190:193], v180 offset:3072
	v_lshl_add_u64 v[186:187], s[2:3], 0, v[176:177]
	s_add_i32 m0, s29, 0xc000
	ds_read_b128 v[194:197], v189
	ds_read_b128 v[198:201], v189 offset:1024
	ds_read_b128 v[202:205], v189 offset:2048
	ds_read_b128 v[206:209], v189 offset:3072
	ds_read_b128 v[210:213], v189 offset:4096
	ds_read_b128 v[214:217], v189 offset:5120
	ds_read_b128 v[230:233], v189 offset:6144
	ds_read_b128 v[234:237], v189 offset:7168
	global_load_lds_dwordx4 v[186:187], off
	v_lshl_add_u64 v[186:187], s[2:3], 0, v[178:179]
	s_add_i32 m0, s29, 0xe000
	s_nop 0
	global_load_lds_dwordx4 v[186:187], off
	s_waitcnt vmcnt(8)
	s_waitcnt lgkmcnt(0)
	s_barrier
	s_waitcnt lgkmcnt(0)
	v_mfma_f32_16x16x32_bf16 v[128:131], v[136:139], v[194:197], v[128:131]
	v_mfma_f32_16x16x32_bf16 v[124:127], v[144:147], v[194:197], v[124:127]
	v_mfma_f32_16x16x32_bf16 v[112:115], v[136:139], v[202:205], v[112:115]
	v_mfma_f32_16x16x32_bf16 v[108:111], v[144:147], v[202:205], v[108:111]
	v_mfma_f32_16x16x32_bf16 v[96:99], v[136:139], v[210:213], v[96:99]
	v_mfma_f32_16x16x32_bf16 v[92:95], v[144:147], v[210:213], v[92:95]
	v_mfma_f32_16x16x32_bf16 v[80:83], v[136:139], v[230:233], v[80:83]
	v_mfma_f32_16x16x32_bf16 v[76:79], v[144:147], v[230:233], v[76:79]
	v_mfma_f32_16x16x32_bf16 v[128:131], v[140:143], v[198:201], v[128:131]
	v_mfma_f32_16x16x32_bf16 v[124:127], v[148:151], v[198:201], v[124:127]
	v_mfma_f32_16x16x32_bf16 v[112:115], v[140:143], v[206:209], v[112:115]
	v_mfma_f32_16x16x32_bf16 v[108:111], v[148:151], v[206:209], v[108:111]
	v_mfma_f32_16x16x32_bf16 v[96:99], v[140:143], v[214:217], v[96:99]
	v_mfma_f32_16x16x32_bf16 v[92:95], v[148:151], v[214:217], v[92:95]
	v_mfma_f32_16x16x32_bf16 v[80:83], v[140:143], v[234:237], v[80:83]
	v_mfma_f32_16x16x32_bf16 v[76:79], v[148:151], v[234:237], v[76:79]
	v_mfma_f32_16x16x32_bf16 v[120:123], v[152:155], v[194:197], v[120:123]
	v_mfma_f32_16x16x32_bf16 v[116:119], v[160:163], v[194:197], v[116:119]
	v_mfma_f32_16x16x32_bf16 v[104:107], v[152:155], v[202:205], v[104:107]
	v_mfma_f32_16x16x32_bf16 v[100:103], v[160:163], v[202:205], v[100:103]
	v_mfma_f32_16x16x32_bf16 v[88:91], v[152:155], v[210:213], v[88:91]
	v_mfma_f32_16x16x32_bf16 v[84:87], v[160:163], v[210:213], v[84:87]
	v_mfma_f32_16x16x32_bf16 v[72:75], v[152:155], v[230:233], v[72:75]
	v_mfma_f32_16x16x32_bf16 v[68:71], v[160:163], v[230:233], v[68:71]
	v_mfma_f32_16x16x32_bf16 v[120:123], v[156:159], v[198:201], v[120:123]
	v_mfma_f32_16x16x32_bf16 v[116:119], v[190:193], v[198:201], v[116:119]
	v_mfma_f32_16x16x32_bf16 v[104:107], v[156:159], v[206:209], v[104:107]
	v_mfma_f32_16x16x32_bf16 v[100:103], v[190:193], v[206:209], v[100:103]
	v_mfma_f32_16x16x32_bf16 v[88:91], v[156:159], v[214:217], v[88:91]
	v_mfma_f32_16x16x32_bf16 v[84:87], v[190:193], v[214:217], v[84:87]
	v_mfma_f32_16x16x32_bf16 v[72:75], v[156:159], v[234:237], v[72:75]
	v_mfma_f32_16x16x32_bf16 v[68:71], v[190:193], v[234:237], v[68:71]
	s_barrier
	s_add_i32 s64, s64, s37
	v_lshl_add_u64 v[186:187], s[30:31], 0, v[164:165]
	s_mov_b32 m0, s64
	ds_read_b128 v[194:197], v189 offset:16384
	ds_read_b128 v[198:201], v189 offset:17408
	ds_read_b128 v[202:205], v189 offset:18432
	ds_read_b128 v[206:209], v189 offset:19456
	ds_read_b128 v[210:213], v189 offset:20480
	ds_read_b128 v[214:217], v189 offset:21504
	ds_read_b128 v[230:233], v189 offset:22528
	ds_read_b128 v[234:237], v189 offset:23552
	global_load_lds_dwordx4 v[186:187], off
	s_add_i32 m0, s64, 0x2000
	s_add_u32 s64, s30, 0x40000
	v_lshl_add_u64 v[238:239], s[30:31], 0, v[168:169]
	s_addc_u32 s65, s31, 0
	s_add_i32 s66, s66, s37
	global_load_lds_dwordx4 v[238:239], off
	v_lshl_add_u64 v[240:241], s[64:65], 0, v[164:165]
	s_mov_b32 m0, s66
	v_lshl_add_u64 v[242:243], s[34:35], 0, v[166:167]
	global_load_lds_dwordx4 v[240:241], off
	v_lshl_add_u64 v[240:241], s[64:65], 0, v[168:169]
	s_add_i32 m0, s66, 0x2000
	s_nop 0
	global_load_lds_dwordx4 v[240:241], off
	v_lshl_add_u64 v[240:241], s[34:35], 0, v[0:1]
	s_mov_b32 m0, s29
	s_nop 0
	global_load_lds_dwordx4 v[240:241], off
	s_mov_b32 m0, s48
	s_nop 0
	global_load_lds_dwordx4 v[242:243], off
	s_waitcnt vmcnt(8)
	s_waitcnt lgkmcnt(0)
	s_barrier
; #define PG8_STAGE(bufoff, gbase, voff) do { _Pragma("unroll") for (int _i = 0; _i < 2; ++_i) \
;         __builtin_amdgcn_global_load_lds((const unsigned*)((const char*)(gbase) + (voff)[_i]), (PG8_LAS unsigned*)(lds + (bufoff) + ldsw + _i * 8192), 16, 0, 0); } while (0)
; #define PG8_LDA(dst, b, h) do { _Pragma("unroll") for (int m = 0; m < 4; ++m) _Pragma("unroll") for (int k = 0; k < 2; ++k) dst[m][k] = *(const PG8_LAS bf16x8*)(lds + PG8_SA(b, h) + aoff + m * 2048 + k * 1024); } while (0)
; #define PG8_LDB(dst, b, h) do { _Pragma("unroll") for (int n = 0; n < 2; ++n) _Pragma("unroll") for (int k = 0; k < 2; ++k) dst[n][k] = *(const PG8_LAS bf16x8*)(lds + PG8_SB(b, h) + boff + n * 2048 + k * 1024); } while (0)
; #define PG8_MMA(ai, bj, At, Bt) do { __builtin_amdgcn_s_setprio(1); _Pragma("unroll") for (int m = 0; m < 4; ++m) _Pragma("unroll") for (int n = 0; n < 2; ++n) _Pragma("unroll") for (int k = 0; k < 2; ++k) \
;         acc[ai][bj][m][n] = __builtin_amdgcn_mfma_f32_16x16x32_bf16(Bt[n][k], At[m][k], acc[ai][bj][m][n], 0, 0, 0); __builtin_amdgcn_s_setprio(0); } while (0)
; #define PG8_WAIT_V(n) asm volatile("s_waitcnt vmcnt(" #n ")" ::: "memory")
; #define PG8_WAIT_L(n) asm volatile("s_waitcnt lgkmcnt(" #n ")" ::: "memory")
; #define PG8_BAR __builtin_amdgcn_s_barrier()
; #define PG8_SCHED __builtin_amdgcn_sched_barrier(0)
; template <class Epi, class Sched, bool ALIGN_EPI = false, bool SP2 = false>
; __device__ __forceinline__ void gemm_phase(PG8_LAS unsigned char* lds, const Gemm g, const Sched& S, const Epi& E) {
;     ...
;             PG8_WAIT_V(8); PG8_WAIT_L(0); PG8_BAR; PG8_MMA(1, 0, At, B0); PG8_MMA(1, 1, At, B1); PG8_BAR; PG8_SCHED;
;             PG8_LDB(B0, 1, 0); PG8_LDB(B1, 1, 1); PG8_SCHED; PG8_LDA(At, 1, 0); PG8_STAGE(PG8_SA(0, 1), a2 + hstep, voffA);
;             PG8_WAIT_V(8); PG8_WAIT_L(0); PG8_BAR; PG8_MMA(0, 0, At, B0); PG8_MMA(0, 1, At, B1); PG8_BAR; PG8_SCHED;
	s_waitcnt lgkmcnt(0)
	v_mfma_f32_16x16x32_bf16 v[64:67], v[136:139], v[194:197], v[64:67]
	v_mfma_f32_16x16x32_bf16 v[60:63], v[144:147], v[194:197], v[60:63]
	v_mfma_f32_16x16x32_bf16 v[48:51], v[136:139], v[202:205], v[48:51]
	v_mfma_f32_16x16x32_bf16 v[44:47], v[144:147], v[202:205], v[44:47]
	v_mfma_f32_16x16x32_bf16 v[32:35], v[136:139], v[210:213], v[32:35]
	v_mfma_f32_16x16x32_bf16 v[28:31], v[144:147], v[210:213], v[28:31]
	v_mfma_f32_16x16x32_bf16 v[16:19], v[136:139], v[230:233], v[16:19]
	v_mfma_f32_16x16x32_bf16 v[12:15], v[144:147], v[230:233], v[12:15]
	v_mfma_f32_16x16x32_bf16 v[64:67], v[140:143], v[198:201], v[64:67]
	v_mfma_f32_16x16x32_bf16 v[60:63], v[148:151], v[198:201], v[60:63]
	v_mfma_f32_16x16x32_bf16 v[48:51], v[140:143], v[206:209], v[48:51]
	v_mfma_f32_16x16x32_bf16 v[44:47], v[148:151], v[206:209], v[44:47]
	v_mfma_f32_16x16x32_bf16 v[32:35], v[140:143], v[214:217], v[32:35]
	v_mfma_f32_16x16x32_bf16 v[28:31], v[148:151], v[214:217], v[28:31]
	v_mfma_f32_16x16x32_bf16 v[16:19], v[140:143], v[234:237], v[16:19]
	v_mfma_f32_16x16x32_bf16 v[12:15], v[148:151], v[234:237], v[12:15]
	v_mfma_f32_16x16x32_bf16 v[56:59], v[152:155], v[194:197], v[56:59]
	v_mfma_f32_16x16x32_bf16 v[52:55], v[160:163], v[194:197], v[52:55]
	v_mfma_f32_16x16x32_bf16 v[40:43], v[152:155], v[202:205], v[40:43]
	v_mfma_f32_16x16x32_bf16 v[36:39], v[160:163], v[202:205], v[36:39]
	v_mfma_f32_16x16x32_bf16 v[24:27], v[152:155], v[210:213], v[24:27]
	v_mfma_f32_16x16x32_bf16 v[20:23], v[160:163], v[210:213], v[20:23]
	v_mfma_f32_16x16x32_bf16 v[8:11], v[152:155], v[230:233], v[8:11]
	v_mfma_f32_16x16x32_bf16 v[4:7], v[160:163], v[230:233], v[4:7]
	v_mfma_f32_16x16x32_bf16 v[56:59], v[156:159], v[198:201], v[56:59]
	v_mfma_f32_16x16x32_bf16 v[52:55], v[190:193], v[198:201], v[52:55]
	v_mfma_f32_16x16x32_bf16 v[40:43], v[156:159], v[206:209], v[40:43]
	v_mfma_f32_16x16x32_bf16 v[36:39], v[190:193], v[206:209], v[36:39]
	v_mfma_f32_16x16x32_bf16 v[24:27], v[156:159], v[214:217], v[24:27]
	v_mfma_f32_16x16x32_bf16 v[20:23], v[190:193], v[214:217], v[20:23]
	v_mfma_f32_16x16x32_bf16 v[8:11], v[156:159], v[234:237], v[8:11]
	v_mfma_f32_16x16x32_bf16 v[4:7], v[190:193], v[234:237], v[4:7]
	s_barrier
	s_add_i32 s64, 0, 0x18000
	s_add_i32 s65, 0, 0x1c000
	v_add_u32_e32 v148, s64, v181
	v_add_u32_e32 v180, s65, v181
	ds_read_b128 v[136:139], v148
	ds_read_b128 v[140:143], v148 offset:1024
	ds_read_b128 v[144:147], v148 offset:2048
	ds_read_b128 v[148:151], v148 offset:3072
	ds_read_b128 v[152:155], v180
	ds_read_b128 v[156:159], v180 offset:1024
	ds_read_b128 v[160:163], v180 offset:2048
	ds_read_b128 v[190:193], v180 offset:3072
	s_add_u32 s34, s34, 0x40000
	s_addc_u32 s35, s35, 0
	s_mov_b32 m0, s49
	v_lshl_add_u64 v[244:245], s[34:35], 0, v[0:1]
	ds_read_b128 v[194:197], v189 offset:32768
	ds_read_b128 v[198:201], v189 offset:33792
	ds_read_b128 v[202:205], v189 offset:34816
	ds_read_b128 v[206:209], v189 offset:35840
	ds_read_b128 v[210:213], v189 offset:36864
	ds_read_b128 v[214:217], v189 offset:37888
	ds_read_b128 v[230:233], v189 offset:38912
	ds_read_b128 v[234:237], v189 offset:39936
	global_load_lds_dwordx4 v[244:245], off
	v_lshl_add_u64 v[244:245], s[34:35], 0, v[166:167]
	s_mov_b32 m0, s50
	s_nop 0
	global_load_lds_dwordx4 v[244:245], off
	s_waitcnt vmcnt(8)
	s_waitcnt lgkmcnt(0)
	s_barrier
	s_waitcnt lgkmcnt(0)
	v_mfma_f32_16x16x32_bf16 v[128:131], v[136:139], v[194:197], v[128:131]
	v_mfma_f32_16x16x32_bf16 v[124:127], v[144:147], v[194:197], v[124:127]
	v_mfma_f32_16x16x32_bf16 v[112:115], v[136:139], v[202:205], v[112:115]
	v_mfma_f32_16x16x32_bf16 v[108:111], v[144:147], v[202:205], v[108:111]
	v_mfma_f32_16x16x32_bf16 v[96:99], v[136:139], v[210:213], v[96:99]
	v_mfma_f32_16x16x32_bf16 v[92:95], v[144:147], v[210:213], v[92:95]
	v_mfma_f32_16x16x32_bf16 v[80:83], v[136:139], v[230:233], v[80:83]
	v_mfma_f32_16x16x32_bf16 v[76:79], v[144:147], v[230:233], v[76:79]
	v_mfma_f32_16x16x32_bf16 v[128:131], v[140:143], v[198:201], v[128:131]
	v_mfma_f32_16x16x32_bf16 v[124:127], v[148:151], v[198:201], v[124:127]
	v_mfma_f32_16x16x32_bf16 v[112:115], v[140:143], v[206:209], v[112:115]
	v_mfma_f32_16x16x32_bf16 v[108:111], v[148:151], v[206:209], v[108:111]
	v_mfma_f32_16x16x32_bf16 v[96:99], v[140:143], v[214:217], v[96:99]
	v_mfma_f32_16x16x32_bf16 v[92:95], v[148:151], v[214:217], v[92:95]
	v_mfma_f32_16x16x32_bf16 v[80:83], v[140:143], v[234:237], v[80:83]
	v_mfma_f32_16x16x32_bf16 v[76:79], v[148:151], v[234:237], v[76:79]
	v_mfma_f32_16x16x32_bf16 v[120:123], v[152:155], v[194:197], v[120:123]
	v_mfma_f32_16x16x32_bf16 v[116:119], v[160:163], v[194:197], v[116:119]
	v_mfma_f32_16x16x32_bf16 v[104:107], v[152:155], v[202:205], v[104:107]
	v_mfma_f32_16x16x32_bf16 v[100:103], v[160:163], v[202:205], v[100:103]
	v_mfma_f32_16x16x32_bf16 v[88:91], v[152:155], v[210:213], v[88:91]
	v_mfma_f32_16x16x32_bf16 v[84:87], v[160:163], v[210:213], v[84:87]
	v_mfma_f32_16x16x32_bf16 v[72:75], v[152:155], v[230:233], v[72:75]
	v_mfma_f32_16x16x32_bf16 v[68:71], v[160:163], v[230:233], v[68:71]
	v_mfma_f32_16x16x32_bf16 v[120:123], v[156:159], v[198:201], v[120:123]
	v_mfma_f32_16x16x32_bf16 v[116:119], v[190:193], v[198:201], v[116:119]
	v_mfma_f32_16x16x32_bf16 v[104:107], v[156:159], v[206:209], v[104:107]
	v_mfma_f32_16x16x32_bf16 v[100:103], v[190:193], v[206:209], v[100:103]
	v_mfma_f32_16x16x32_bf16 v[88:91], v[156:159], v[214:217], v[88:91]
	v_mfma_f32_16x16x32_bf16 v[84:87], v[190:193], v[214:217], v[84:87]
	v_mfma_f32_16x16x32_bf16 v[72:75], v[156:159], v[234:237], v[72:75]
	v_mfma_f32_16x16x32_bf16 v[68:71], v[190:193], v[234:237], v[68:71]
	s_barrier
; #define PG8_STAGE(bufoff, gbase, voff) do { _Pragma("unroll") for (int _i = 0; _i < 2; ++_i) \
;         __builtin_amdgcn_global_load_lds((const unsigned*)((const char*)(gbase) + (voff)[_i]), (PG8_LAS unsigned*)(lds + (bufoff) + ldsw + _i * 8192), 16, 0, 0); } while (0)
; #define PG8_LDA(dst, b, h) do { _Pragma("unroll") for (int m = 0; m < 4; ++m) _Pragma("unroll") for (int k = 0; k < 2; ++k) dst[m][k] = *(const PG8_LAS bf16x8*)(lds + PG8_SA(b, h) + aoff + m * 2048 + k * 1024); } while (0)
; #define PG8_MMA(ai, bj, At, Bt) do { __builtin_amdgcn_s_setprio(1); _Pragma("unroll") for (int m = 0; m < 4; ++m) _Pragma("unroll") for (int n = 0; n < 2; ++n) _Pragma("unroll") for (int k = 0; k < 2; ++k) \
;         acc[ai][bj][m][n] = __builtin_amdgcn_mfma_f32_16x16x32_bf16(Bt[n][k], At[m][k], acc[ai][bj][m][n], 0, 0, 0); __builtin_amdgcn_s_setprio(0); } while (0)
; #define PG8_WAIT_V(n) asm volatile("s_waitcnt vmcnt(" #n ")" ::: "memory")
; #define PG8_WAIT_L(n) asm volatile("s_waitcnt lgkmcnt(" #n ")" ::: "memory")
; #define PG8_BAR __builtin_amdgcn_s_barrier()
; #define PG8_SCHED __builtin_amdgcn_sched_barrier(0)
; template <class Epi, class Sched, bool ALIGN_EPI = false, bool SP2 = false>
; __device__ __forceinline__ void gemm_phase(PG8_LAS unsigned char* lds, const Gemm g, const Sched& S, const Epi& E) {
;     ...
;         for (int t = 0; t < nt; t += 2) {
;     ...
;             PG8_LDA(At, 1, 1); PG8_STAGE(PG8_SB(1, 0), b3, voffB); PG8_STAGE(PG8_SB(1, 1), b3 + hstep, voffB); PG8_STAGE(PG8_SA(1, 0), a3, voffA);
;             PG8_WAIT_V(8); PG8_WAIT_L(0); PG8_BAR; PG8_MMA(1, 0, At, B0); PG8_MMA(1, 1, At, B1); PG8_BAR; PG8_SCHED;
	s_add_i32 s34, s64, s37
	v_lshl_add_u64 v[186:187], v[186:187], 0, s[96:97]
	s_mov_b32 m0, s34
	ds_read_b128 v[194:197], v189 offset:49152
	ds_read_b128 v[198:201], v189 offset:50176
	ds_read_b128 v[202:205], v189 offset:51200
	ds_read_b128 v[206:209], v189 offset:52224
	ds_read_b128 v[210:213], v189 offset:53248
	ds_read_b128 v[214:217], v189 offset:54272
	ds_read_b128 v[230:233], v189 offset:55296
	ds_read_b128 v[234:237], v189 offset:56320
	global_load_lds_dwordx4 v[186:187], off
	s_add_i32 m0, s34, 0x2000
	s_add_u32 s30, s30, 0x40080
	v_lshl_add_u64 v[186:187], v[238:239], 0, s[96:97]
	s_addc_u32 s31, s31, 0
	s_add_i32 s34, s65, s37
	global_load_lds_dwordx4 v[186:187], off
	v_lshl_add_u64 v[186:187], s[30:31], 0, v[164:165]
	s_mov_b32 m0, s34
	s_nop 0
	global_load_lds_dwordx4 v[186:187], off
	v_lshl_add_u64 v[186:187], s[30:31], 0, v[168:169]
	s_add_i32 m0, s34, 0x2000
	s_nop 0
	global_load_lds_dwordx4 v[186:187], off
	v_lshl_add_u64 v[186:187], v[240:241], 0, s[96:97]
	s_mov_b32 m0, s51
	s_nop 0
	global_load_lds_dwordx4 v[186:187], off
	v_lshl_add_u64 v[186:187], v[242:243], 0, s[96:97]
	s_mov_b32 m0, s52
	s_nop 0
	global_load_lds_dwordx4 v[186:187], off
	s_waitcnt vmcnt(8)
	s_waitcnt lgkmcnt(0)
	s_barrier
	s_waitcnt lgkmcnt(0)
	v_mfma_f32_16x16x32_bf16 v[64:67], v[136:139], v[194:197], v[64:67]
	v_mfma_f32_16x16x32_bf16 v[60:63], v[144:147], v[194:197], v[60:63]
	v_mfma_f32_16x16x32_bf16 v[48:51], v[136:139], v[202:205], v[48:51]
	v_mfma_f32_16x16x32_bf16 v[44:47], v[144:147], v[202:205], v[44:47]
	v_mfma_f32_16x16x32_bf16 v[32:35], v[136:139], v[210:213], v[32:35]
	v_mfma_f32_16x16x32_bf16 v[28:31], v[144:147], v[210:213], v[28:31]
	v_mfma_f32_16x16x32_bf16 v[16:19], v[136:139], v[230:233], v[16:19]
	v_mfma_f32_16x16x32_bf16 v[12:15], v[144:147], v[230:233], v[12:15]
	v_mfma_f32_16x16x32_bf16 v[64:67], v[140:143], v[198:201], v[64:67]
	v_mfma_f32_16x16x32_bf16 v[60:63], v[148:151], v[198:201], v[60:63]
	v_mfma_f32_16x16x32_bf16 v[48:51], v[140:143], v[206:209], v[48:51]
	v_mfma_f32_16x16x32_bf16 v[44:47], v[148:151], v[206:209], v[44:47]
	v_mfma_f32_16x16x32_bf16 v[32:35], v[140:143], v[214:217], v[32:35]
	v_mfma_f32_16x16x32_bf16 v[28:31], v[148:151], v[214:217], v[28:31]
	v_mfma_f32_16x16x32_bf16 v[16:19], v[140:143], v[234:237], v[16:19]
	v_mfma_f32_16x16x32_bf16 v[12:15], v[148:151], v[234:237], v[12:15]
	v_mfma_f32_16x16x32_bf16 v[56:59], v[152:155], v[194:197], v[56:59]
	v_mfma_f32_16x16x32_bf16 v[52:55], v[160:163], v[194:197], v[52:55]
	v_mfma_f32_16x16x32_bf16 v[40:43], v[152:155], v[202:205], v[40:43]
	v_mfma_f32_16x16x32_bf16 v[36:39], v[160:163], v[202:205], v[36:39]
	v_mfma_f32_16x16x32_bf16 v[24:27], v[152:155], v[210:213], v[24:27]
	v_mfma_f32_16x16x32_bf16 v[20:23], v[160:163], v[210:213], v[20:23]
	v_mfma_f32_16x16x32_bf16 v[8:11], v[152:155], v[230:233], v[8:11]
	v_mfma_f32_16x16x32_bf16 v[4:7], v[160:163], v[230:233], v[4:7]
	v_mfma_f32_16x16x32_bf16 v[56:59], v[156:159], v[198:201], v[56:59]
	v_mfma_f32_16x16x32_bf16 v[52:55], v[190:193], v[198:201], v[52:55]
	v_mfma_f32_16x16x32_bf16 v[40:43], v[156:159], v[206:209], v[40:43]
	v_mfma_f32_16x16x32_bf16 v[36:39], v[190:193], v[206:209], v[36:39]
	v_mfma_f32_16x16x32_bf16 v[24:27], v[156:159], v[214:217], v[24:27]
	v_mfma_f32_16x16x32_bf16 v[20:23], v[190:193], v[214:217], v[20:23]
	v_mfma_f32_16x16x32_bf16 v[8:11], v[156:159], v[234:237], v[8:11]
	v_mfma_f32_16x16x32_bf16 v[4:7], v[190:193], v[234:237], v[4:7]
	s_barrier
	s_add_i32 s62, s62, 2
	s_add_u32 s2, s2, 0x100
	s_addc_u32 s3, s3, 0
	s_add_u32 s60, s60, 0x100
	s_addc_u32 s61, s61, 0
	s_cmp_gt_u32 s62, 13
	s_cbranch_scc1 .LBB0_515
